# attention: stagger the two wave halves - waves 0-3 take the per-tile barrier after the last PV MFMA, waves 4-7 keep it mid-block, so co-resident waves stop running MFMA/VALU phases in lockstep
# speedup vs baseline: 1.0195x; 1.0195x over previous
; #define AT_WAIT_BAR() asm volatile("s_waitcnt vmcnt(0) lgkmcnt(0)\n\ts_barrier" ::: "memory")
; #define AT_DMAK(t_) do { const bf16_t* gb_ = kgb + (size_t)(t_) * 64 * 512; const unsigned d_ = (unsigned)__builtin_amdgcn_readfirstlane(lds0 + ((t_) % 3) * AT_KB + dmaoff); glds16(kvo0, gb_, d_); glds16(kvo1, gb_, d_ + 8192u); } while (0)
; #define AT_DMAV(t_) do { const bf16_t* gb_ = vgb + (size_t)(t_) * 64 * 512; const unsigned d_ = (unsigned)__builtin_amdgcn_readfirstlane(lds0 + AT_V0 + ((t_) & 1) * AT_VB + dmaoff); glds16(vvo0, gb_, d_); glds16(vvo1, gb_, d_ + 8192u); } while (0)
; #define AT_SETCLS(u_) do { const int nc_ = AT_CLS(u_); if (nc_ != ccls) { const float d_ = (nc_ == 0 ? bleft : (nc_ == 2 ? bright : 0.f)) - (ccls == 0 ? bleft : (ccls == 2 ? bright : 0.f)); \
;             _Pragma("unroll") for (int i = 0; i < 16; ++i) negc[i] += d_; ccls = nc_; } } while (0)
; __device__ __forceinline__ void attn_phase(LAS unsigned char* lds, const bf16_t* QA, const bf16_t* KA, const bf16_t* VA, bf16_t* CAT, const bf16_t* OF, const bf16_t* OB, const bf16_t* GR, const float* rnorm, ...
;     ...
;         const int unit = it * 256 + vcu, bh = unit >> 5, qb = unit & 31, b = bh >> 2, hd = bh & 3;
;         const size_t tok0 = (size_t)b * SEQ;
;         const int q0 = qb * 128 + qw * 32;
;         bf16x8 qf[4];
;         { const bf16_t* qp = QA + (tok0 + q0 + r) * 512 + hd * 128 + c * 64 + 8 * h;
; #pragma unroll
;           for (int d0 = 0; d0 < 4; ++d0) qf[d0] = *(const bf16x8*)(qp + 16 * d0); }
;         f32x16 o[4], negc;
; #pragma unroll
;         for (int i = 0; i < 16; ++i) { o[0][i] = 0.f; o[1][i] = 0.f; o[2][i] = 0.f; o[3][i] = 0.f; negc[i] = 0.f; }
;         float lsum = 0.f;
;         const bf16_t* kgb = KA + tok0 * 512 + hd * 128; const bf16_t* vgb = VA + tok0 * 512 + hd * 128;
;     ...
;         AT_DMAK(0); AT_DMAV(0); AT_DMAK(1);
;         AT_WAIT_BAR();
;         const float bleft = tab[hd * 324 + 0], bright = tab[hd * 324 + 320];
;     ...
;         int ccls = 1;
;     ...
;         f32x16 sA, sB;
; #pragma unroll
;         for (int i = 0; i < 16; ++i) sB[i] = 0.f;
;         AT_SETCLS(0); AT_QK(sA, 0);
.LBB0_586:
	s_bitcmp1_b32 s82, 12
	s_cselect_b64 s[98:99], -1, 0
	s_lshl_b32 s0, s31, 8
	s_add_i32 s0, s0, s63
	s_ashr_i32 s0, s0, 7
	s_ashr_i32 s1, s0, 31
	s_lshl_b64 s[34:35], s[0:1], 12
	v_mov_b32_e32 v159, s35
	v_or_b32_e32 v158, s34, v144
	v_lshlrev_b64 v[0:1], 10, v[158:159]
	v_lshl_add_u64 v[0:1], v[146:147], 0, v[0:1]
	global_load_dwordx4 v[140:143], v[0:1], off
	global_load_dwordx4 v[136:139], v[0:1], off offset:32
	global_load_dwordx4 v[132:135], v[0:1], off offset:64
	global_load_dwordx4 v[128:131], v[0:1], off offset:96
	s_lshl_b64 s[0:1], s[0:1], 22
	s_add_u32 s6, s40, s0
	s_addc_u32 s7, s41, s1
	s_add_u32 s0, s42, s0
	s_mov_b32 s8, m0
	s_mov_b32 m0, s82
	s_nop 0
	global_load_lds_dwordx4 v174, s[6:7]
	s_mov_b32 m0, s8
	s_addc_u32 s1, s43, s1
	s_add_i32 s8, s82, 0x2000
	s_mov_b32 s9, m0
	s_mov_b32 m0, s8
	s_nop 0
	global_load_lds_dwordx4 v180, s[6:7]
	s_mov_b32 m0, s9
	s_add_i32 s33, s82, 0xe000
	s_mov_b32 s9, m0
	s_mov_b32 m0, s83
	s_nop 0
	global_load_lds_dwordx4 v175, s[0:1]
	s_mov_b32 m0, s9
	s_add_u32 s8, s6, 0x10000
	s_mov_b32 s38, m0
	s_mov_b32 m0, s33
	s_nop 0
	global_load_lds_dwordx4 v181, s[0:1]
	s_mov_b32 m0, s38
	s_addc_u32 s9, s7, 0
	s_add_i32 s36, s82, 0x4000
	s_mov_b32 s33, m0
	s_mov_b32 m0, s36
	s_nop 0
	global_load_lds_dwordx4 v174, s[8:9]
	s_mov_b32 m0, s33
	s_add_i32 s37, s82, 0x6000
	s_mov_b32 s33, m0
	s_mov_b32 m0, s37
	s_nop 0
	global_load_lds_dwordx4 v180, s[8:9]
	s_mov_b32 m0, s33
	v_mov_b32_e32 v0, s67
	s_waitcnt vmcnt(0) lgkmcnt(0)
	s_barrier
	ds_read2st64_b32 v[160:161], v0 offset1:5
	ds_read_b128 v[0:3], v196
	ds_read_b128 v[4:7], v197
	s_add_u32 s8, s6, 0x20000
	s_addc_u32 s9, s7, 0
	s_waitcnt lgkmcnt(2)
	v_add_f32_e32 v8, 0, v160
	v_cndmask_b32_e64 v64, v8, 0, s[14:15]
	v_mov_b32_e32 v65, v64
	v_mov_b32_e32 v66, v64
	v_mov_b32_e32 v67, v64
	v_mov_b32_e32 v68, v64
	v_mov_b32_e32 v69, v64
	v_mov_b32_e32 v70, v64
	v_mov_b32_e32 v71, v64
	v_mov_b32_e32 v72, v64
	v_mov_b32_e32 v73, v64
	v_mov_b32_e32 v74, v64
	v_mov_b32_e32 v75, v64
	v_mov_b32_e32 v76, v64
	v_mov_b32_e32 v77, v64
	v_mov_b32_e32 v78, v64
	v_mov_b32_e32 v79, v64
	s_add_i32 s33, s82, 0x8000
	s_add_i32 s38, s82, 0xa000
	s_add_u32 s36, s0, 0x10000
	s_addc_u32 s37, s1, 0
	s_add_i32 s39, s82, 0x10000
	s_andn2_b64 vcc, exec, s[24:25]
	s_waitcnt vmcnt(3) lgkmcnt(1)
	v_mfma_f32_32x32x16_bf16 v[86:101], v[0:3], v[140:143], v[64:79]
	ds_read_b128 v[0:3], v204
	s_waitcnt vmcnt(2) lgkmcnt(1)
	v_mfma_f32_32x32x16_bf16 v[86:101], v[4:7], v[136:139], v[86:101]
	ds_read_b128 v[4:7], v205
	s_mov_b32 s46, m0
	s_mov_b32 m0, s33
	s_nop 0
	global_load_lds_dwordx4 v174, s[8:9]
	s_mov_b32 m0, s46
	s_mov_b32 s33, m0
	s_mov_b32 m0, s38
	s_nop 0
	global_load_lds_dwordx4 v180, s[8:9]
	s_mov_b32 m0, s33
	s_mov_b32 s8, m0
	s_mov_b32 m0, s39
	s_nop 0
	global_load_lds_dwordx4 v175, s[36:37]
	s_mov_b32 m0, s8
	s_add_i32 s8, s82, 0x12000
	s_mov_b32 s9, m0
	s_mov_b32 m0, s8
	s_nop 0
	global_load_lds_dwordx4 v181, s[36:37]
	s_mov_b32 m0, s9
	s_waitcnt vmcnt(1) lgkmcnt(1)
	v_mfma_f32_32x32x16_bf16 v[86:101], v[0:3], v[132:135], v[86:101]
	s_waitcnt vmcnt(0) lgkmcnt(0)
	v_mfma_f32_32x32x16_bf16 v[86:101], v[4:7], v[128:131], v[86:101]
	s_cbranch_vccnz .LBB0_588
	v_cndmask_b32_e64 v0, v160, 0, s[20:21]
	v_cndmask_b32_e64 v1, v160, 0, s[14:15]
	v_sub_f32_e32 v0, v0, v1
	v_mov_b32_e32 v2, v64
	v_mov_b32_e32 v3, v64
	v_pk_add_f32 v[66:67], v[0:1], v[2:3] op_sel_hi:[0,1]
	v_pk_add_f32 v[64:65], v[0:1], v[64:65] op_sel_hi:[0,1]
	v_mov_b32_e32 v68, v66
	v_mov_b32_e32 v69, v67
	v_mov_b32_e32 v70, v66
	v_mov_b32_e32 v71, v67
	v_mov_b32_e32 v72, v66
	v_mov_b32_e32 v73, v67
	v_mov_b32_e32 v74, v66
	v_mov_b32_e32 v75, v67
	v_mov_b32_e32 v76, v66
	v_mov_b32_e32 v77, v67
	v_mov_b32_e32 v78, v66
	v_mov_b32_e32 v79, v67
	s_mov_b64 s[8:9], s[20:21]
	s_andn2_b64 vcc, exec, s[14:15]
	s_cbranch_vccz .LBB0_589
	s_branch .LBB0_590

.LBB0_597:
	s_and_b64 vcc, exec, s[98:99]
	ds_read_b64_tr_b16 v[100:101], v207 offset:57344
	ds_read_b64_tr_b16 v[102:103], v207 offset:59392
	v_cvt_pk_bf16_f32 v96, v112, v113
	v_cvt_pk_bf16_f32 v97, v116, v115
	v_cvt_pk_bf16_f32 v98, v118, v119
	v_cvt_pk_bf16_f32 v99, v120, v117
	ds_read_b64_tr_b16 v[104:105], v207 offset:61440
	ds_read_b64_tr_b16 v[106:107], v207 offset:63488
	s_waitcnt lgkmcnt(2)
	v_mfma_f32_32x32x16_bf16 v[48:63], v[100:103], v[96:99], v[48:63]
	ds_read_b64_tr_b16 v[100:101], v208 offset:57344
	ds_read_b64_tr_b16 v[102:103], v208 offset:59392
	ds_read_b64_tr_b16 v[108:109], v208 offset:61440
	ds_read_b64_tr_b16 v[110:111], v208 offset:63488
	s_add_i32 s65, s65, 1
	s_add_u32 s36, s36, 0x10000
	s_addc_u32 s37, s37, 0
	s_addk_i32 s69, 0x4000
	s_add_i32 s70, s70, 64
	s_add_u32 s38, s38, 0x10000
	s_waitcnt lgkmcnt(2)
	v_mfma_f32_32x32x16_bf16 v[32:47], v[100:103], v[96:99], v[32:47]
	ds_read_b64_tr_b16 v[100:101], v206 offset:57344
	ds_read_b64_tr_b16 v[102:103], v206 offset:59392
	ds_read_b64_tr_b16 v[116:117], v206 offset:61440
	ds_read_b64_tr_b16 v[118:119], v206 offset:63488
	s_addc_u32 s39, s39, 0
	s_add_i32 s71, s71, 1
	s_add_i32 s46, s46, 1
	v_add_f32_e32 v162, v163, v162
	s_cmp_eq_u32 s69, 0x100000
	s_waitcnt lgkmcnt(2)
	v_mfma_f32_32x32x16_bf16 v[16:31], v[100:103], v[96:99], v[16:31]
	ds_read_b64_tr_b16 v[100:101], v164 offset:57344
	ds_read_b64_tr_b16 v[102:103], v164 offset:59392
	ds_read_b64_tr_b16 v[206:207], v164 offset:61440
	ds_read_b64_tr_b16 v[208:209], v164 offset:63488
	s_cbranch_vccz .Lat_skip_p1
	s_waitcnt vmcnt(0) lgkmcnt(0)
	s_barrier
.Lat_skip_p1:
	s_waitcnt lgkmcnt(2)
	v_mfma_f32_32x32x16_bf16 v[0:15], v[100:103], v[96:99], v[0:15]
	v_cvt_pk_bf16_f32 v96, v114, v121
	v_cvt_pk_bf16_f32 v97, v122, v123
	v_cvt_pk_bf16_f32 v98, v124, v125
	v_cvt_pk_bf16_f32 v99, v126, v127
	s_nop 1
	v_mfma_f32_32x32x16_bf16 v[48:63], v[104:107], v[96:99], v[48:63]
	v_mfma_f32_32x32x16_bf16 v[32:47], v[108:111], v[96:99], v[32:47]
	v_mfma_f32_32x32x16_bf16 v[16:31], v[116:119], v[96:99], v[16:31]
	s_waitcnt lgkmcnt(0)
	v_mfma_f32_32x32x16_bf16 v[0:15], v[206:209], v[96:99], v[0:15]
	s_cbranch_vccnz .Lat_skip_p0
	s_waitcnt vmcnt(0) lgkmcnt(0)
	s_barrier
.Lat_skip_p0:
	s_cbranch_scc1 .LBB0_614

; template <int LO, int HI>
; __global__ void __launch_bounds__(512, 2) mega(Params p) {
;     extern __shared__ __attribute__((aligned(16))) unsigned char lds_raw[];
	.amdhsa_kernel _Z4megaILi0ELi9EEv6Params
		.amdhsa_group_segment_fixed_size 0
		.amdhsa_private_segment_fixed_size 0
		.amdhsa_kernarg_size 440
		.amdhsa_user_sgpr_count 2
		.amdhsa_user_sgpr_dispatch_ptr 0
		.amdhsa_user_sgpr_queue_ptr 0
		.amdhsa_user_sgpr_kernarg_segment_ptr 1
		.amdhsa_user_sgpr_dispatch_id 0
		.amdhsa_user_sgpr_kernarg_preload_length 0
		.amdhsa_user_sgpr_kernarg_preload_offset 0
		.amdhsa_user_sgpr_private_segment_size 0
		.amdhsa_uses_dynamic_stack 0
		.amdhsa_enable_private_segment 0
		.amdhsa_system_sgpr_workgroup_id_x 1
		.amdhsa_system_sgpr_workgroup_id_y 0
		.amdhsa_system_sgpr_workgroup_id_z 0
		.amdhsa_system_sgpr_workgroup_info 0
		.amdhsa_system_vgpr_workitem_id 2
		.amdhsa_next_free_vgpr 256
		.amdhsa_next_free_sgpr 100
		.amdhsa_accum_offset 256
		.amdhsa_reserve_vcc 1
		.amdhsa_float_round_mode_32 0
		.amdhsa_float_round_mode_16_64 0
		.amdhsa_float_denorm_mode_32 3
		.amdhsa_float_denorm_mode_16_64 3
		.amdhsa_dx10_clamp 1
		.amdhsa_ieee_mode 1
		.amdhsa_fp16_overflow 0
		.amdhsa_tg_split 0
		.amdhsa_exception_fp_ieee_invalid_op 0
		.amdhsa_exception_fp_denorm_src 0
		.amdhsa_exception_fp_ieee_div_zero 0
		.amdhsa_exception_fp_ieee_overflow 0
		.amdhsa_exception_fp_ieee_underflow 0
		.amdhsa_exception_fp_ieee_inexact 0
		.amdhsa_exception_int_div_zero 0
	.end_amdhsa_kernel

; template <int LO, int HI>
; __global__ void __launch_bounds__(512, 2) mega(Params p) {
amdhsa.kernels:
  - .agpr_count:     0
    .args:
      - .offset:         0
        .size:           184
        .value_kind:     by_value
      - .offset:         184
        .size:           4
        .value_kind:     hidden_block_count_x
      - .offset:         188
        .size:           4
        .value_kind:     hidden_block_count_y
      - .offset:         192
        .size:           4
        .value_kind:     hidden_block_count_z
      - .offset:         196
        .size:           2
        .value_kind:     hidden_group_size_x
      - .offset:         198
        .size:           2
        .value_kind:     hidden_group_size_y
      - .offset:         200
        .size:           2
        .value_kind:     hidden_group_size_z
      - .offset:         202
        .size:           2
        .value_kind:     hidden_remainder_x
      - .offset:         204
        .size:           2
        .value_kind:     hidden_remainder_y
      - .offset:         206
        .size:           2
        .value_kind:     hidden_remainder_z
      - .offset:         224
        .size:           8
        .value_kind:     hidden_global_offset_x
      - .offset:         232
        .size:           8
        .value_kind:     hidden_global_offset_y
      - .offset:         240
        .size:           8
        .value_kind:     hidden_global_offset_z
      - .offset:         248
        .size:           2
        .value_kind:     hidden_grid_dims
      - .offset:         272
        .size:           8
        .value_kind:     hidden_multigrid_sync_arg
      - .offset:         304
        .size:           4
        .value_kind:     hidden_dynamic_lds_size
    .group_segment_fixed_size: 0
    .kernarg_segment_align: 8
    .kernarg_segment_size: 440
    .language:       OpenCL C
    .language_version:
      - 2
      - 0
    .max_flat_workgroup_size: 512
    .name:           _Z4megaILi0ELi9EEv6Params
    .private_segment_fixed_size: 0
    .sgpr_count:     106
    .sgpr_spill_count: 68
    .symbol:         _Z4megaILi0ELi9EEv6Params.kd
    .uniform_work_group_size: 1
    .uses_dynamic_stack: false
    .vgpr_count:     256
    .vgpr_spill_count: 0
    .wavefront_size: 64
